# prologue weight transpose: batch the 16 gain+weight loads per half-tile behind one wait instead of a wait per element
# speedup vs baseline: 1.0264x; 1.0136x over previous
; __device__ __forceinline__ void tr_item(const float* W, int ldw, int srccol0, const float* g0, const float* g1, int gsplit, bf16_t* WT, int K, int k0, int dstrow0, LAS float* scr, int lane) {
;     ...
; #pragma unroll 16
;         for (int i = 0; i < 32; ++i) { const int kk = 2 * i + (lane >> 5), k = k0 + kk; float gv = 1.f; if (g0) gv = (k < gsplit) ? g0[k] : g1[k - gsplit];
;             scr[kk * 33 + (lane & 31)] = W[(size_t)k * ldw + srccol0 + (lane & 31)] * gv; }
.LBB0_902:
	v_mov_b32_e32 v215, 1.0
.LBB0_903:
	v_mad_u64_u32 v[28:29], s[24:25], v16, s45, 0
	v_mov_b32_e32 v16, v29
	v_mad_u64_u32 v[30:31], s[24:25], v3, s45, v[16:17]
	v_mov_b32_e32 v29, v30
	v_lshl_add_u64 v[28:29], v[28:29], 2, v[12:13]
	global_load_dword v231, v[28:29], off
	s_add_i32 s10, s10, 32
	s_cmp_eq_u32 s10, 64
	v_lshl_add_u64 v[14:15], v[14:15], 0, s[14:15]
	s_waitcnt vmcnt(0)
	v_mul_f32_e32 v216, v200, v216
	ds_write_b32 v26, v216
	v_mul_f32_e32 v217, v201, v217
	ds_write_b32 v26, v217 offset:264
	v_mul_f32_e32 v218, v202, v218
	ds_write_b32 v26, v218 offset:528
	v_mul_f32_e32 v219, v203, v219
	ds_write_b32 v26, v219 offset:792
	v_mul_f32_e32 v220, v204, v220
	ds_write_b32 v26, v220 offset:1056
	v_mul_f32_e32 v221, v205, v221
	ds_write_b32 v26, v221 offset:1320
	v_mul_f32_e32 v222, v206, v222
	ds_write_b32 v26, v222 offset:1584
	v_mul_f32_e32 v223, v207, v223
	ds_write_b32 v26, v223 offset:1848
	v_mul_f32_e32 v224, v208, v224
	ds_write_b32 v26, v224 offset:2112
	v_mul_f32_e32 v225, v209, v225
	ds_write_b32 v26, v225 offset:2376
	v_mul_f32_e32 v226, v210, v226
	ds_write_b32 v26, v226 offset:2640
	v_mul_f32_e32 v227, v211, v227
	ds_write_b32 v26, v227 offset:2904
	v_mul_f32_e32 v228, v212, v228
	ds_write_b32 v26, v228 offset:3168
	v_mul_f32_e32 v229, v213, v229
	ds_write_b32 v26, v229 offset:3432
	v_mul_f32_e32 v230, v214, v230
	ds_write_b32 v26, v230 offset:3696
	v_mul_f32_e32 v231, v215, v231
	ds_write_b32 v26, v231 offset:3960
	v_add_u32_e32 v26, 0x1080, v26
	s_cbranch_scc1 .LBB0_872
.LBB0_904:
	v_add_u32_e32 v16, s10, v9
	s_and_b64 vcc, exec, s[34:35]
	v_ashrrev_i32_e32 v17, 31, v16
	s_cbranch_vccz .LBB0_951
	v_add_u32_e32 v132, s10, v25
	v_lshl_add_u64 v[28:29], v[16:17], 2, s[8:9]
	v_lshl_add_u64 v[30:31], v[132:133], 2, s[6:7]
	v_cmp_gt_i32_e32 vcc, s44, v16
	s_nop 1
	v_cndmask_b32_e32 v29, v31, v29, vcc
	v_cndmask_b32_e32 v28, v30, v28, vcc
	global_load_dword v200, v[28:29], off
	s_cbranch_execnz .LBB0_907
.LBB0_906:
	v_mov_b32_e32 v200, 1.0
.LBB0_907:
	v_mad_u64_u32 v[28:29], s[24:25], v16, s45, 0
	v_mov_b32_e32 v18, v29
	v_mad_u64_u32 v[30:31], s[24:25], v17, s45, v[18:19]
	v_mov_b32_e32 v29, v30
	v_lshl_add_u64 v[28:29], v[28:29], 2, v[12:13]
	global_load_dword v216, v[28:29], off
	v_add_u32_e32 v18, 2, v16
	v_cndmask_b32_e64 v27, 0, 1, s[34:35]
	v_cmp_ne_u32_e64 s[40:41], 1, v27
	s_andn2_b64 vcc, exec, s[34:35]
	v_ashrrev_i32_e32 v3, 31, v18
	s_cbranch_vccnz .LBB0_952
	s_movk_i32 s24, 0xff90
	s_mov_b32 s25, -1
	v_add3_u32 v132, v25, s10, 2
	v_lshl_add_u64 v[28:29], v[14:15], 0, s[24:25]
	v_lshl_add_u64 v[30:31], v[132:133], 2, s[6:7]
	v_cmp_gt_i32_e32 vcc, s44, v18
	s_nop 1
	v_cndmask_b32_e32 v29, v31, v29, vcc
	v_cndmask_b32_e32 v28, v30, v28, vcc
	global_load_dword v201, v[28:29], off
	s_cbranch_execnz .LBB0_910
.LBB0_909:
	v_mov_b32_e32 v201, 1.0
.LBB0_910:
	v_mad_u64_u32 v[28:29], s[24:25], v18, s45, 0
	v_mov_b32_e32 v18, v29
	v_mad_u64_u32 v[30:31], s[24:25], v3, s45, v[18:19]
	v_mov_b32_e32 v29, v30
	v_lshl_add_u64 v[28:29], v[28:29], 2, v[12:13]
	global_load_dword v217, v[28:29], off
	v_add_u32_e32 v18, 4, v16
	s_and_b64 vcc, exec, s[40:41]
	v_ashrrev_i32_e32 v3, 31, v18
	s_cbranch_vccnz .LBB0_953
	s_movk_i32 s24, 0xff98
	s_mov_b32 s25, -1
	v_add3_u32 v132, v25, s10, 4
	v_lshl_add_u64 v[28:29], v[14:15], 0, s[24:25]
	v_lshl_add_u64 v[30:31], v[132:133], 2, s[6:7]
	v_cmp_gt_i32_e32 vcc, s44, v18
	s_nop 1
	v_cndmask_b32_e32 v29, v31, v29, vcc
	v_cndmask_b32_e32 v28, v30, v28, vcc
	global_load_dword v202, v[28:29], off
	s_cbranch_execnz .LBB0_913
.LBB0_912:
	v_mov_b32_e32 v202, 1.0
.LBB0_913:
	v_mad_u64_u32 v[28:29], s[24:25], v18, s45, 0
	v_mov_b32_e32 v18, v29
	v_mad_u64_u32 v[30:31], s[24:25], v3, s45, v[18:19]
	v_mov_b32_e32 v29, v30
	v_lshl_add_u64 v[28:29], v[28:29], 2, v[12:13]
	global_load_dword v218, v[28:29], off
	v_add_u32_e32 v18, 6, v16
	s_and_b64 vcc, exec, s[40:41]
	v_ashrrev_i32_e32 v3, 31, v18
	s_cbranch_vccnz .LBB0_954
	s_movk_i32 s24, 0xffa0
	s_mov_b32 s25, -1
	v_add3_u32 v132, v25, s10, 6
	v_lshl_add_u64 v[28:29], v[14:15], 0, s[24:25]
	v_lshl_add_u64 v[30:31], v[132:133], 2, s[6:7]
	v_cmp_gt_i32_e32 vcc, s44, v18
	s_nop 1
	v_cndmask_b32_e32 v29, v31, v29, vcc
	v_cndmask_b32_e32 v28, v30, v28, vcc
	global_load_dword v203, v[28:29], off
	s_cbranch_execnz .LBB0_916
.LBB0_915:
	v_mov_b32_e32 v203, 1.0
.LBB0_916:
	v_mad_u64_u32 v[28:29], s[24:25], v18, s45, 0
	v_mov_b32_e32 v18, v29
	v_mad_u64_u32 v[30:31], s[24:25], v3, s45, v[18:19]
	v_mov_b32_e32 v29, v30
	v_lshl_add_u64 v[28:29], v[28:29], 2, v[12:13]
	global_load_dword v219, v[28:29], off
	v_add_u32_e32 v18, 8, v16
	s_and_b64 vcc, exec, s[40:41]
	v_ashrrev_i32_e32 v3, 31, v18
	s_cbranch_vccnz .LBB0_955
	s_movk_i32 s24, 0xffa8
	s_mov_b32 s25, -1
	v_add3_u32 v132, v25, s10, 8
	v_lshl_add_u64 v[28:29], v[14:15], 0, s[24:25]
	v_lshl_add_u64 v[30:31], v[132:133], 2, s[6:7]
	v_cmp_gt_i32_e32 vcc, s44, v18
	s_nop 1
	v_cndmask_b32_e32 v29, v31, v29, vcc
	v_cndmask_b32_e32 v28, v30, v28, vcc
	global_load_dword v204, v[28:29], off
	s_cbranch_execnz .LBB0_919
.LBB0_918:
	v_mov_b32_e32 v204, 1.0
.LBB0_919:
	v_mad_u64_u32 v[28:29], s[24:25], v18, s45, 0
	v_mov_b32_e32 v18, v29
	v_mad_u64_u32 v[30:31], s[24:25], v3, s45, v[18:19]
	v_mov_b32_e32 v29, v30
	v_lshl_add_u64 v[28:29], v[28:29], 2, v[12:13]
	global_load_dword v220, v[28:29], off
	v_add_u32_e32 v18, 10, v16
	s_and_b64 vcc, exec, s[40:41]
	v_ashrrev_i32_e32 v3, 31, v18
	s_cbranch_vccnz .LBB0_956
	s_movk_i32 s24, 0xffb0
	s_mov_b32 s25, -1
	v_add3_u32 v132, v25, s10, 10
	v_lshl_add_u64 v[28:29], v[14:15], 0, s[24:25]
	v_lshl_add_u64 v[30:31], v[132:133], 2, s[6:7]
	v_cmp_gt_i32_e32 vcc, s44, v18
	s_nop 1
	v_cndmask_b32_e32 v29, v31, v29, vcc
	v_cndmask_b32_e32 v28, v30, v28, vcc
	global_load_dword v205, v[28:29], off
	s_cbranch_execnz .LBB0_922
; __device__ __forceinline__ void tr_item(const float* W, int ldw, int srccol0, const float* g0, const float* g1, int gsplit, bf16_t* WT, int K, int k0, int dstrow0, LAS float* scr, int lane) {
;     ...
; #pragma unroll 16
;         for (int i = 0; i < 32; ++i) { const int kk = 2 * i + (lane >> 5), k = k0 + kk; float gv = 1.f; if (g0) gv = (k < gsplit) ? g0[k] : g1[k - gsplit];
;             scr[kk * 33 + (lane & 31)] = W[(size_t)k * ldw + srccol0 + (lane & 31)] * gv; }
.LBB0_921:
	v_mov_b32_e32 v205, 1.0
.LBB0_922:
	v_mad_u64_u32 v[28:29], s[24:25], v18, s45, 0
	v_mov_b32_e32 v18, v29
	v_mad_u64_u32 v[30:31], s[24:25], v3, s45, v[18:19]
	v_mov_b32_e32 v29, v30
	v_lshl_add_u64 v[28:29], v[28:29], 2, v[12:13]
	global_load_dword v221, v[28:29], off
	v_add_u32_e32 v18, 12, v16
	s_and_b64 vcc, exec, s[40:41]
	v_ashrrev_i32_e32 v3, 31, v18
	s_cbranch_vccnz .LBB0_957
	s_movk_i32 s24, 0xffb8
	s_mov_b32 s25, -1
	v_add3_u32 v132, v25, s10, 12
	v_lshl_add_u64 v[28:29], v[14:15], 0, s[24:25]
	v_lshl_add_u64 v[30:31], v[132:133], 2, s[6:7]
	v_cmp_gt_i32_e32 vcc, s44, v18
	s_nop 1
	v_cndmask_b32_e32 v29, v31, v29, vcc
	v_cndmask_b32_e32 v28, v30, v28, vcc
	global_load_dword v206, v[28:29], off
	s_cbranch_execnz .LBB0_925
.LBB0_924:
	v_mov_b32_e32 v206, 1.0
.LBB0_925:
	v_mad_u64_u32 v[28:29], s[24:25], v18, s45, 0
	v_mov_b32_e32 v18, v29
	v_mad_u64_u32 v[30:31], s[24:25], v3, s45, v[18:19]
	v_mov_b32_e32 v29, v30
	v_lshl_add_u64 v[28:29], v[28:29], 2, v[12:13]
	global_load_dword v222, v[28:29], off
	v_add_u32_e32 v18, 14, v16
	s_and_b64 vcc, exec, s[40:41]
	v_ashrrev_i32_e32 v3, 31, v18
	s_cbranch_vccnz .LBB0_958
	s_movk_i32 s24, 0xffc0
	s_mov_b32 s25, -1
	v_add3_u32 v132, v25, s10, 14
	v_lshl_add_u64 v[28:29], v[14:15], 0, s[24:25]
	v_lshl_add_u64 v[30:31], v[132:133], 2, s[6:7]
	v_cmp_gt_i32_e32 vcc, s44, v18
	s_nop 1
	v_cndmask_b32_e32 v29, v31, v29, vcc
	v_cndmask_b32_e32 v28, v30, v28, vcc
	global_load_dword v207, v[28:29], off
	s_cbranch_execnz .LBB0_928
.LBB0_927:
	v_mov_b32_e32 v207, 1.0
.LBB0_928:
	v_mad_u64_u32 v[28:29], s[24:25], v18, s45, 0
	v_mov_b32_e32 v18, v29
	v_mad_u64_u32 v[30:31], s[24:25], v3, s45, v[18:19]
	v_mov_b32_e32 v29, v30
	v_lshl_add_u64 v[28:29], v[28:29], 2, v[12:13]
	global_load_dword v223, v[28:29], off
	v_add_u32_e32 v18, 16, v16
	s_and_b64 vcc, exec, s[40:41]
	v_ashrrev_i32_e32 v3, 31, v18
	s_cbranch_vccnz .LBB0_959
	s_movk_i32 s24, 0xffc8
	s_mov_b32 s25, -1
	v_add3_u32 v132, v25, s10, 16
	v_lshl_add_u64 v[28:29], v[14:15], 0, s[24:25]
	v_lshl_add_u64 v[30:31], v[132:133], 2, s[6:7]
	v_cmp_gt_i32_e32 vcc, s44, v18
	s_nop 1
	v_cndmask_b32_e32 v29, v31, v29, vcc
	v_cndmask_b32_e32 v28, v30, v28, vcc
	global_load_dword v208, v[28:29], off
	s_cbranch_execnz .LBB0_931
.LBB0_930:
	v_mov_b32_e32 v208, 1.0
.LBB0_931:
	v_mad_u64_u32 v[28:29], s[24:25], v18, s45, 0
	v_mov_b32_e32 v18, v29
	v_mad_u64_u32 v[30:31], s[24:25], v3, s45, v[18:19]
	v_mov_b32_e32 v29, v30
	v_lshl_add_u64 v[28:29], v[28:29], 2, v[12:13]
	global_load_dword v224, v[28:29], off
	v_add_u32_e32 v18, 18, v16
	s_and_b64 vcc, exec, s[40:41]
	v_ashrrev_i32_e32 v3, 31, v18
	s_cbranch_vccnz .LBB0_960
	s_movk_i32 s24, 0xffd0
	s_mov_b32 s25, -1
	v_add3_u32 v132, v25, s10, 18
	v_lshl_add_u64 v[28:29], v[14:15], 0, s[24:25]
	v_lshl_add_u64 v[30:31], v[132:133], 2, s[6:7]
	v_cmp_gt_i32_e32 vcc, s44, v18
	s_nop 1
	v_cndmask_b32_e32 v29, v31, v29, vcc
	v_cndmask_b32_e32 v28, v30, v28, vcc
	global_load_dword v209, v[28:29], off
	s_cbranch_execnz .LBB0_934
.LBB0_933:
	v_mov_b32_e32 v209, 1.0
.LBB0_934:
	v_mad_u64_u32 v[28:29], s[24:25], v18, s45, 0
	v_mov_b32_e32 v18, v29
	v_mad_u64_u32 v[30:31], s[24:25], v3, s45, v[18:19]
	v_mov_b32_e32 v29, v30
	v_lshl_add_u64 v[28:29], v[28:29], 2, v[12:13]
	global_load_dword v225, v[28:29], off
	v_add_u32_e32 v18, 20, v16
	s_and_b64 vcc, exec, s[40:41]
	v_ashrrev_i32_e32 v3, 31, v18
	s_cbranch_vccnz .LBB0_961
	s_movk_i32 s24, 0xffd8
	s_mov_b32 s25, -1
	v_add3_u32 v132, v25, s10, 20
	v_lshl_add_u64 v[28:29], v[14:15], 0, s[24:25]
	v_lshl_add_u64 v[30:31], v[132:133], 2, s[6:7]
	v_cmp_gt_i32_e32 vcc, s44, v18
	s_nop 1
	v_cndmask_b32_e32 v29, v31, v29, vcc
	v_cndmask_b32_e32 v28, v30, v28, vcc
	global_load_dword v210, v[28:29], off
	s_cbranch_execnz .LBB0_937
; __device__ __forceinline__ void tr_item(const float* W, int ldw, int srccol0, const float* g0, const float* g1, int gsplit, bf16_t* WT, int K, int k0, int dstrow0, LAS float* scr, int lane) {
;     ...
; #pragma unroll 16
;         for (int i = 0; i < 32; ++i) { const int kk = 2 * i + (lane >> 5), k = k0 + kk; float gv = 1.f; if (g0) gv = (k < gsplit) ? g0[k] : g1[k - gsplit];
;             scr[kk * 33 + (lane & 31)] = W[(size_t)k * ldw + srccol0 + (lane & 31)] * gv; }
.LBB0_936:
	v_mov_b32_e32 v210, 1.0
.LBB0_937:
	v_mad_u64_u32 v[28:29], s[24:25], v18, s45, 0
	v_mov_b32_e32 v18, v29
	v_mad_u64_u32 v[30:31], s[24:25], v3, s45, v[18:19]
	v_mov_b32_e32 v29, v30
	v_lshl_add_u64 v[28:29], v[28:29], 2, v[12:13]
	global_load_dword v226, v[28:29], off
	v_add_u32_e32 v18, 22, v16
	s_and_b64 vcc, exec, s[40:41]
	v_ashrrev_i32_e32 v3, 31, v18
	s_cbranch_vccnz .LBB0_962
	s_movk_i32 s24, 0xffe0
	s_mov_b32 s25, -1
	v_add3_u32 v132, v25, s10, 22
	v_lshl_add_u64 v[28:29], v[14:15], 0, s[24:25]
	v_lshl_add_u64 v[30:31], v[132:133], 2, s[6:7]
	v_cmp_gt_i32_e32 vcc, s44, v18
	s_nop 1
	v_cndmask_b32_e32 v29, v31, v29, vcc
	v_cndmask_b32_e32 v28, v30, v28, vcc
	global_load_dword v211, v[28:29], off
	s_cbranch_execnz .LBB0_940
.LBB0_939:
	v_mov_b32_e32 v211, 1.0
.LBB0_940:
	v_mad_u64_u32 v[28:29], s[24:25], v18, s45, 0
	v_mov_b32_e32 v18, v29
	v_mad_u64_u32 v[30:31], s[24:25], v3, s45, v[18:19]
	v_mov_b32_e32 v29, v30
	v_lshl_add_u64 v[28:29], v[28:29], 2, v[12:13]
	global_load_dword v227, v[28:29], off
	v_add_u32_e32 v18, 24, v16
	s_and_b64 vcc, exec, s[40:41]
	v_ashrrev_i32_e32 v3, 31, v18
	s_cbranch_vccnz .LBB0_963
	s_movk_i32 s24, 0xffe8
	s_mov_b32 s25, -1
	v_add3_u32 v132, v25, s10, 24
	v_lshl_add_u64 v[28:29], v[14:15], 0, s[24:25]
	v_lshl_add_u64 v[30:31], v[132:133], 2, s[6:7]
	v_cmp_gt_i32_e32 vcc, s44, v18
	s_nop 1
	v_cndmask_b32_e32 v29, v31, v29, vcc
	v_cndmask_b32_e32 v28, v30, v28, vcc
	global_load_dword v212, v[28:29], off
	s_cbranch_execnz .LBB0_943
.LBB0_942:
	v_mov_b32_e32 v212, 1.0
.LBB0_943:
	v_mad_u64_u32 v[28:29], s[24:25], v18, s45, 0
	v_mov_b32_e32 v18, v29
	v_mad_u64_u32 v[30:31], s[24:25], v3, s45, v[18:19]
	v_mov_b32_e32 v29, v30
	v_lshl_add_u64 v[28:29], v[28:29], 2, v[12:13]
	global_load_dword v228, v[28:29], off
	v_add_u32_e32 v18, 26, v16
	s_and_b64 vcc, exec, s[40:41]
	v_ashrrev_i32_e32 v3, 31, v18
	s_cbranch_vccnz .LBB0_964
	v_add3_u32 v132, v25, s10, 26
	v_lshl_add_u64 v[28:29], v[14:15], 0, -16
	v_lshl_add_u64 v[30:31], v[132:133], 2, s[6:7]
	v_cmp_gt_i32_e32 vcc, s44, v18
	s_nop 1
	v_cndmask_b32_e32 v29, v31, v29, vcc
	v_cndmask_b32_e32 v28, v30, v28, vcc
	global_load_dword v213, v[28:29], off
	s_cbranch_execnz .LBB0_946
.LBB0_945:
	v_mov_b32_e32 v213, 1.0
.LBB0_946:
	v_mad_u64_u32 v[28:29], s[24:25], v18, s45, 0
	v_mov_b32_e32 v18, v29
	v_mad_u64_u32 v[30:31], s[24:25], v3, s45, v[18:19]
	v_mov_b32_e32 v29, v30
	v_lshl_add_u64 v[28:29], v[28:29], 2, v[12:13]
	global_load_dword v229, v[28:29], off
	v_add_u32_e32 v18, 28, v16
	s_and_b64 vcc, exec, s[40:41]
	v_ashrrev_i32_e32 v3, 31, v18
	s_cbranch_vccnz .LBB0_965
	v_add3_u32 v132, v25, s10, 28
	v_lshl_add_u64 v[28:29], v[14:15], 0, -8
	v_lshl_add_u64 v[30:31], v[132:133], 2, s[6:7]
	v_cmp_gt_i32_e32 vcc, s44, v18
	s_nop 1
	v_cndmask_b32_e32 v29, v31, v29, vcc
	v_cndmask_b32_e32 v28, v30, v28, vcc
	global_load_dword v214, v[28:29], off
	s_cbranch_execnz .LBB0_949
.LBB0_948:
	v_mov_b32_e32 v214, 1.0
.LBB0_949:
	v_mad_u64_u32 v[28:29], s[24:25], v18, s45, 0
	v_mov_b32_e32 v18, v29
	v_mad_u64_u32 v[30:31], s[24:25], v3, s45, v[18:19]
	v_mov_b32_e32 v29, v30
	v_lshl_add_u64 v[28:29], v[28:29], 2, v[12:13]
	global_load_dword v230, v[28:29], off
	v_add_u32_e32 v16, 30, v16
	s_and_b64 vcc, exec, s[40:41]
	v_ashrrev_i32_e32 v3, 31, v16
	s_cbranch_vccnz .LBB0_966
	v_add3_u32 v132, v25, s10, 30
	v_lshl_add_u64 v[28:29], v[132:133], 2, s[6:7]
	v_cmp_gt_i32_e32 vcc, s44, v16
	s_nop 1
	v_cndmask_b32_e32 v29, v29, v15, vcc
	v_cndmask_b32_e32 v28, v28, v14, vcc
	global_load_dword v215, v[28:29], off
	s_cbranch_execnz .LBB0_903
	s_branch .LBB0_902
